# attention loops: two K/V tiles per workgroup barrier (pair iterations), 12 tiles DMA-ahead
# speedup vs baseline: 1.0310x; 1.0039x over previous
.LBB0_801:
	s_add_i32 m0, s18, 0xc000
	s_nop 0
	global_load_lds_dwordx4 v[146:147], off
	v_lshl_add_u64 v[146:147], v[146:147], 0, s[20:21]
	s_add_i32 m0, s18, 0xe000
	s_nop 0
	global_load_lds_dwordx4 v[146:147], off
	v_lshl_add_u64 v[146:147], v[146:147], 0, s[20:21]
	s_cmp_eq_u32 s49, 8
	s_cbranch_scc1 .Lmob_pk8
	s_add_i32 m0, s18, 0x10000
	s_nop 0
	global_load_lds_dwordx4 v[146:147], off
	v_lshl_add_u64 v[146:147], v[146:147], 0, s[20:21]
	s_add_i32 m0, s18, 0x12000
	s_nop 0
	global_load_lds_dwordx4 v[146:147], off
	v_lshl_add_u64 v[146:147], v[146:147], 0, s[20:21]
	s_add_i32 m0, s18, 0x14000
	s_nop 0
	global_load_lds_dwordx4 v[146:147], off
	v_lshl_add_u64 v[146:147], v[146:147], 0, s[20:21]
	s_add_i32 m0, s18, 0x16000
	s_nop 0
	global_load_lds_dwordx4 v[146:147], off
	v_lshl_add_u64 v[146:147], v[146:147], 0, s[20:21]
	s_branch .Lmob_pk14
.Lmob_pk8:
.Lmob_pk14:
	v_add_u32_e32 v216, v166, v165
	v_add_u32_e32 v217, v167, v165
	v_add_u32_e32 v218, v168, v165
	v_add_u32_e32 v219, v169, v165
	v_add_u32_e32 v220, v170, v171
	v_add_u32_e32 v221, v170, v172
	v_mov_b32_e32 v123, 0xff800000
	s_cmp_eq_u32 s49, 8
	s_cbranch_scc1 .Lmob_pw7
	s_waitcnt vmcnt(11)
	s_branch .Lmob_pbar

.Lmob_top_e:
	s_add_i32 s40, s69, 12
	s_cmp_ge_u32 s40, s49
	s_cbranch_scc1 .Lmob_noissue_e
	s_and_b32 s40, s40, 15
	s_lshl_b32 s40, s40, 13
	s_add_i32 m0, s40, s18
	v_lshl_add_u64 v[120:121], v[146:147], 0, s[20:21]
	global_load_lds_dwordx4 v[146:147], off
	s_add_i32 m0, m0, 0x2000
	s_nop 0
	global_load_lds_dwordx4 v[120:121], off
.Lmob_noissue_e:
	s_cmp_gt_i32 s70, 12
	s_cbranch_scc1 .Lmob_w11_e
	s_cmp_gt_i32 s70, 8
	s_cbranch_scc1 .Lmob_w7_e
	s_cmp_gt_i32 s70, 4
	s_cbranch_scc1 .Lmob_w3_e
	s_cmp_gt_i32 s70, 2
	s_cbranch_scc1 .Lmob_w1_e
	s_waitcnt vmcnt(0)
	s_branch .Lmob_bar_e

.Lmob_w7_e:
	s_waitcnt vmcnt(7)
	s_branch .Lmob_bar_e
.Lmob_w11_e:
	s_waitcnt vmcnt(11)

.Lmob_top_o:
	s_cmp_gt_i32 s69, s68
	s_cbranch_scc1 .Lmob_next_o
	s_and_b32 s40, s69, 15
	s_lshl_b32 s40, s40, 13
	s_cmp_eq_u32 s69, s68
	s_cbranch_scc1 .Lmob_last_o
	s_add_i32 s41, s69, 1
	s_and_b32 s41, s41, 15
	s_lshl_b32 s41, s41, 13
	s_cmp_lt_u32 s69, s67
	s_cbranch_scc1 .Lmob_lane_o
	v_add_u32_e32 v103, s41, v216
	ds_read_b128 v[66:69], v103
	v_add_u32_e32 v103, s41, v217
	ds_read_b128 v[70:73], v103
	v_add_u32_e32 v103, s41, v218
	ds_read_b128 v[74:77], v103
	v_add_u32_e32 v103, s41, v219
	ds_read_b128 v[78:81], v103
	v_add_u32_e32 v103, s40, v220
	ds_read_b128 v[104:107], v103 offset:4096
	ds_read_b128 v[108:111], v103 offset:6144
	v_add_u32_e32 v103, s40, v221
	ds_read_b128 v[112:115], v103 offset:4096
	ds_read_b128 v[116:119], v103 offset:6144
	v_max_f32_e32 v99, v201, v201
	v_max_f32_e32 v100, v200, v200
	v_max_f32_e32 v99, v100, v99
	v_max3_f32 v99, v99, v202, v203
	v_max3_f32 v99, v99, v204, v205
	v_max3_f32 v99, v99, v206, v207
	v_max3_f32 v99, v99, v208, v209
	v_max3_f32 v99, v99, v210, v211
	v_max3_f32 v99, v99, v212, v213
	v_max3_f32 v99, v99, v214, v215
	s_waitcnt lgkmcnt(4)
	v_mfma_f32_32x32x16_bf16 v[34:49], v[66:69], v[82:85], 0
	v_mov_b32_e32 v100, v99
	s_nop 1
	v_permlane32_swap_b32_e32 v99, v100
	v_max_f32_e32 v100, v100, v100
	v_max_f32_e32 v99, v99, v99
	v_max_f32_e32 v99, v99, v100
	v_mfma_f32_32x32x16_bf16 v[34:49], v[70:73], v[86:89], v[34:49]
	v_add_f32_e32 v100, 0x42317218, v176
	v_cmp_gt_f32_e32 vcc, v99, v100
	s_cbranch_vccnz .Lmob_rare_fbo

.Lmob_next_o:
	s_add_i32 s69, s69, 1
	s_add_i32 s70, s70, -1
	v_subrev_u32_e32 v145, 32, v145
	s_cmp_lg_u32 s70, -1
	v_lshl_add_u64 v[146:147], v[146:147], 0, s[20:21]
	v_lshl_add_u64 v[146:147], v[146:147], 0, s[20:21]
	s_cbranch_scc0 .LBB0_836
	s_branch .Lmob_top_e

.Ldsa_pk8:
	s_mov_b64 s[40:41], 0xc000
	v_lshl_add_u64 v[86:87], v[2:3], 0, s[40:41]
	s_add_i32 s53, s68, 7
	s_mov_b32 s65, 0
	v_mov_b32_e32 v0, 0
	v_mov_b64_e32 v[2:3], v[0:1]
	v_mov_b64_e32 v[4:5], v[0:1]
	v_mov_b64_e32 v[6:7], v[0:1]
	v_mov_b64_e32 v[8:9], v[0:1]
	v_mov_b64_e32 v[10:11], v[0:1]
	v_mov_b64_e32 v[12:13], v[0:1]
	v_mov_b64_e32 v[14:15], v[0:1]
	v_mov_b64_e32 v[16:17], v[0:1]
	v_mov_b64_e32 v[18:19], v[0:1]
	v_mov_b64_e32 v[20:21], v[0:1]
	v_mov_b64_e32 v[22:23], v[0:1]
	v_mov_b64_e32 v[24:25], v[0:1]
	v_mov_b64_e32 v[26:27], v[0:1]
	v_mov_b64_e32 v[28:29], v[0:1]
	v_mov_b64_e32 v[30:31], v[0:1]
	v_mov_b64_e32 v[32:33], v[0:1]
	v_mov_b32_e32 v83, 0xf149f2ca
	v_mov_b32_e32 v141, 0
	v_add_u32_e32 v216, v166, v165
	v_add_u32_e32 v217, v167, v165
	v_add_u32_e32 v218, v168, v165
	v_add_u32_e32 v219, v169, v165
	v_add_u32_e32 v220, v170, v171
	v_add_u32_e32 v221, v170, v172
	v_lshl_add_u32 v222, s1, 5, v135
	v_lshlrev_b32_e32 v222, 4, v222
	s_cmp_eq_u32 s52, 8
	s_cbranch_scc1 .Ldsa_pw7
	s_waitcnt vmcnt(11)
	s_branch .Ldsa_pbar

.Ldsa_top_e:
	s_add_i32 s40, s65, 12
	s_cmp_ge_u32 s40, s52
	s_cbranch_scc1 .Ldsa_noissue_e
	s_and_b32 s40, s40, 15
	s_lshl_b32 s40, s40, 13
	s_add_i32 m0, s40, s18
	v_lshl_add_u64 v[126:127], v[86:87], 0, s[20:21]
	global_load_lds_dwordx4 v[86:87], off
	s_add_i32 m0, m0, 0x2000
	s_nop 0
	global_load_lds_dwordx4 v[126:127], off
.Ldsa_noissue_e:
	s_cmp_gt_i32 s53, 12
	s_cbranch_scc1 .Ldsa_w11_e
	s_cmp_gt_i32 s53, 8
	s_cbranch_scc1 .Ldsa_w7_e
	s_cmp_gt_i32 s53, 4
	s_cbranch_scc1 .Ldsa_w3_e
	s_cmp_gt_i32 s53, 2
	s_cbranch_scc1 .Ldsa_w1_e
	s_waitcnt vmcnt(0)
	s_branch .Ldsa_bar_e

.Ldsa_top_o:
	s_cmp_gt_i32 s65, s67
	s_cbranch_scc1 .Ldsa_next_o
	s_and_b32 s40, s65, 15
	s_lshl_b32 s40, s40, 13
	s_lshl_b32 s66, s65, 10
	s_and_b32 s66, s66, 0x3000
	s_and_b32 s41, s65, 3
	s_lshl_b32 s41, s41, 2
	s_add_i32 s66, s66, s41
	s_add_i32 s66, s66, 0x20020
	s_cmp_eq_u32 s65, s67
	s_cbranch_scc1 .Ldsa_last_o
	s_add_i32 s41, s65, 1
	s_and_b32 s41, s41, 15
	s_lshl_b32 s41, s41, 13
	v_add_u32_e32 v125, s41, v216
	ds_read_b128 v[66:69], v125
	v_add_u32_e32 v125, s41, v217
	ds_read_b128 v[70:73], v125
	v_add_u32_e32 v125, s41, v218
	ds_read_b128 v[74:77], v125
	v_add_u32_e32 v125, s41, v219
	ds_read_b128 v[78:81], v125
	v_add_u32_e32 v125, s40, v220
	ds_read_b128 v[104:107], v125 offset:4096
	ds_read_b128 v[108:111], v125 offset:6144
	v_add_u32_e32 v125, s40, v221
	ds_read_b128 v[112:115], v125 offset:4096
	ds_read_b128 v[116:119], v125 offset:6144
	v_add_u32_e32 v125, s66, v222
	ds_read_b32 v124, v125
	v_max_f32_e32 v121, v201, v201
	v_max_f32_e32 v122, v200, v200
	v_max_f32_e32 v121, v122, v121
	v_max3_f32 v121, v121, v202, v203
	v_max3_f32 v121, v121, v204, v205
	v_max3_f32 v121, v121, v206, v207
	v_max3_f32 v121, v121, v208, v209
	v_max3_f32 v121, v121, v210, v211
	v_max3_f32 v121, v121, v212, v213
	v_max3_f32 v121, v121, v214, v215
	s_waitcnt lgkmcnt(5)
	v_mfma_f32_32x32x16_bf16 v[34:49], v[66:69], v[50:53], 0
	v_mov_b32_e32 v122, v121
	s_nop 1
	v_permlane32_swap_b32_e32 v121, v122
	v_max_f32_e32 v122, v122, v122
	v_max_f32_e32 v121, v121, v121
	v_max_f32_e32 v121, v121, v122
	v_mfma_f32_32x32x16_bf16 v[34:49], v[70:73], v[54:57], v[34:49]
	v_add_f32_e32 v122, 0x42317218, v83
	v_cmp_gt_f32_e32 vcc, v121, v122
	s_cbranch_vccnz .Ldsa_rare_fbo

.Ldsa_next_o:
	s_add_i32 s65, s65, 1
	s_add_i32 s53, s53, -1
	s_cmp_lg_u32 s53, -1
	v_lshl_add_u64 v[86:87], v[86:87], 0, s[20:21]
	v_lshl_add_u64 v[86:87], v[86:87], 0, s[20:21]
	s_cbranch_scc0 .LBB0_788
	s_branch .Ldsa_top_e
